# P5 live variant: last K iteration's dummy next-unit staging loads point at the XN residual tile (L2 prefetch for the epilogue's LDS-DMA residual fetch)
# baseline (speedup 1.0000x reference)
;     __host__ __device__ bool next(int i, Unit& u) const { return at((long)i * G + c, u); }
;     __host__ __device__ bool next(int i, Unit& u) const { if (i != 0 || c >= cnt) return false; u.pm = pm0 + c / nN; u.pn = c % nN; u.k0 = 0; u.nt = ntk; return true; }
;     ...
;         const bool has_next = S.next(ui + 1, nxt);
;         const char* nA = has_next ? (const char*)g.A + (size_t)nxt.pm * tstep + (size_t)nxt.k0 * (BK * 2) : cA; const char* nB = has_next ? (const char*)g.Bt + (size_t)nxt.pn * tstep + (size_t)nxt.k0 * (BK * 2) : cB;
;         const int nt = cur.nt;
;         for (int t = 0; t < nt; t += 2) {
;             const bool last = (t == nt - 2);
;             const char* a1 = cA + (size_t)(t + 1) * kstep;
;             const char* a2 = last ? nA : cA + (size_t)(t + 2) * kstep; const char* b2 = last ? nB : cB + (size_t)(t + 2) * kstep;
;             const char* a3 = a2 + kstep; const char* b3 = b2 + kstep;
.LBB0_887:
	s_add_u32 s54, s36, 0x100
	s_addc_u32 s55, s37, 0
	s_ashr_i32 s27, s26, 31
	s_lshl_b64 s[28:29], s[26:27], 19
	s_add_u32 s28, s6, s28
	s_addc_u32 s29, s7, s29
	s_and_b64 s[30:31], s[4:5], exec
	s_cselect_b32 s27, s29, s35
	s_cselect_b32 s56, s28, s34
	s_ashr_i32 s25, s24, 31
	s_lshl_b64 s[30:31], s[24:25], 19
	s_add_u32 s30, s3, s30
	s_addc_u32 s31, s42, s31
	s_and_b64 s[38:39], s[4:5], exec
	s_cselect_b32 s25, s31, s37
	s_cselect_b32 s57, s30, s36
	s_sub_u32 s76, s34, s6
	s_sub_u32 s77, s36, s3
	s_lshr_b32 s77, s77, 10
	s_add_u32 s76, s76, s77
	s_add_u32 s76, s76, 0x1a00000
	s_add_u32 s98, s68, s76
	s_addc_u32 s99, s69, 0
	s_and_b64 s[38:39], s[4:5], exec
	s_cselect_b32 s56, s56, s98
	s_cselect_b32 s27, s27, s99
	s_add_u32 s98, s98, 0x100
	s_addc_u32 s99, s99, 0
	s_and_b64 s[38:39], s[4:5], exec
	s_cselect_b32 s57, s57, s98
	s_cselect_b32 s25, s25, s99
	v_lshl_add_u64 v[142:143], s[34:35], 0, v[136:137]
	v_lshl_add_u64 v[144:145], s[34:35], 0, v[138:139]
	s_mov_b32 s58, -2
	s_mov_b64 s[36:37], 0
	v_readlane_b32 s98, v255, 17
	s_cmp_lg_u32 s98, 1
	s_cbranch_scc1 .Lsprio_4
	s_setprio 1
